# P2 epilogue waits only for its own (hoisted, long complete) row-statistic loads: vmcnt(16) instead of vmcnt(0), so the next unit's prefetch DMA stays in flight through the epilogue
# baseline (speedup 1.0000x reference)
.LBB0_191:
	s_sub_i32 s21, s29, 32
	s_cmp_lt_u32 s21, 16
	s_cbranch_scc1 .Lp2_vepi
	v_lshl_add_u32 v144, s28, 8, v146
	v_ashrrev_i32_e32 v145, 31, v144
	v_lshl_add_u64 v[154:155], v[144:145], 2, s[8:9]
	v_or_b32_e32 v156, 16, v144
	v_ashrrev_i32_e32 v157, 31, v156
	v_or_b32_e32 v160, 32, v144
	v_lshl_add_u64 v[158:159], v[156:157], 2, s[8:9]
	v_ashrrev_i32_e32 v161, 31, v160
	v_lshl_add_u64 v[162:163], v[160:161], 2, s[8:9]
	v_or_b32_e32 v158, 48, v144
	v_ashrrev_i32_e32 v159, 31, v158
	v_lshl_add_u64 v[162:163], v[158:159], 2, s[8:9]
	s_ashr_i32 s21, s29, 31
	s_lshr_b32 s21, s21, 28
	s_add_i32 s21, s29, s21
	s_add_i32 s23, s29, 15
	s_ashr_i32 s28, s21, 4
	s_cmp_lt_u32 s23, 31
	v_lshl_add_u32 v167, s29, 8, v148
	s_cselect_b64 vcc, -1, 0
	s_ashr_i32 s29, s28, 31
	s_lshl_b64 s[30:31], s[28:29], 27
	s_add_u32 s30, s42, s30
	s_addc_u32 s31, s43, s31
	s_lshl_b32 s21, s28, 12
	v_subrev_u32_e32 v154, s21, v167
	v_cndmask_b32_e32 v174, 1.0, v153, vcc
	v_ashrrev_i32_e32 v155, 31, v154
	v_lshlrev_b64 v[144:145], 13, v[144:145]
	v_lshl_add_u64 v[154:155], v[154:155], 1, s[30:31]
	v_lshl_add_u64 v[144:145], v[154:155], 0, v[144:145]
	v_lshlrev_b64 v[156:157], 13, v[156:157]
	v_lshl_add_u64 v[156:157], v[154:155], 0, v[156:157]
	v_lshlrev_b64 v[160:161], 13, v[160:161]
	v_lshl_add_u64 v[160:161], v[154:155], 0, v[160:161]
	s_waitcnt vmcnt(16)
	v_fmamk_f32 v162, v228, 0x39800000, v152
	v_rsq_f32_e32 v162, v162
	v_fmamk_f32 v163, v229, 0x39800000, v152
	v_fmamk_f32 v164, v230, 0x39800000, v152
	v_rsq_f32_e32 v166, v163
	v_rsq_f32_e32 v167, v164
	v_mul_f32_e32 v162, v174, v162
	v_pk_mul_f32 v[122:123], v[122:123], v[162:163] op_sel_hi:[1,0]
	v_mul_f32_e32 v166, v174, v166
	v_pk_mul_f32 v[126:127], v[126:127], v[162:163] op_sel_hi:[1,0]
	v_pk_mul_f32 v[124:125], v[124:125], v[162:163] op_sel_hi:[1,0]
	v_pk_mul_f32 v[120:121], v[120:121], v[162:163] op_sel_hi:[1,0]
	v_pk_mul_f32 v[110:111], v[110:111], v[162:163] op_sel_hi:[1,0]
	v_pk_mul_f32 v[108:109], v[108:109], v[162:163] op_sel_hi:[1,0]
	v_pk_mul_f32 v[164:165], v[102:103], v[162:163] op_sel_hi:[1,0]
	v_pk_mul_f32 v[162:163], v[100:101], v[162:163] op_sel_hi:[1,0]
	v_cvt_pk_bf16_f32 v100, v124, v125
	v_cvt_pk_bf16_f32 v101, v126, v127
	v_cvt_pk_bf16_f32 v102, v120, v121
	v_cvt_pk_bf16_f32 v103, v122, v123
	v_pk_mul_f32 v[122:123], v[88:89], v[166:167] op_sel_hi:[1,0]
	global_store_dwordx4 v[144:145], v[100:103], off
	v_cvt_pk_bf16_f32 v88, v108, v109
	v_cvt_pk_bf16_f32 v89, v110, v111
	v_pk_mul_f32 v[118:119], v[118:119], v[166:167] op_sel_hi:[1,0]
	v_pk_mul_f32 v[116:117], v[116:117], v[166:167] op_sel_hi:[1,0]
	v_pk_mul_f32 v[120:121], v[90:91], v[166:167] op_sel_hi:[1,0]
	v_cvt_pk_bf16_f32 v90, v162, v163
	v_cvt_pk_bf16_f32 v91, v164, v165
	global_store_dwordx4 v[144:145], v[88:91], off offset:256
	v_mul_f32_e32 v168, v174, v167
	v_pk_mul_f32 v[114:115], v[114:115], v[166:167] op_sel_hi:[1,0]
	v_cvt_pk_bf16_f32 v88, v116, v117
	v_cvt_pk_bf16_f32 v89, v118, v119
	v_pk_mul_f32 v[112:113], v[112:113], v[166:167] op_sel_hi:[1,0]
	v_pk_mul_f32 v[94:95], v[94:95], v[166:167] op_sel_hi:[1,0]
	v_pk_mul_f32 v[92:93], v[92:93], v[166:167] op_sel_hi:[1,0]
	v_cvt_pk_bf16_f32 v90, v112, v113
	v_cvt_pk_bf16_f32 v91, v114, v115
	global_store_dwordx4 v[156:157], v[88:91], off
	v_pk_mul_f32 v[106:107], v[106:107], v[168:169] op_sel_hi:[1,0]
	v_pk_mul_f32 v[104:105], v[104:105], v[168:169] op_sel_hi:[1,0]
	v_cvt_pk_bf16_f32 v88, v92, v93
	v_cvt_pk_bf16_f32 v89, v94, v95
	v_cvt_pk_bf16_f32 v90, v122, v123
	v_cvt_pk_bf16_f32 v91, v120, v121
	global_store_dwordx4 v[156:157], v[88:91], off offset:256
	v_pk_mul_f32 v[84:85], v[84:85], v[168:169] op_sel_hi:[1,0]
	v_pk_mul_f32 v[98:99], v[98:99], v[168:169] op_sel_hi:[1,0]
	v_cvt_pk_bf16_f32 v88, v104, v105
	v_cvt_pk_bf16_f32 v89, v106, v107
	v_pk_mul_f32 v[96:97], v[96:97], v[168:169] op_sel_hi:[1,0]
	v_pk_mul_f32 v[86:87], v[86:87], v[168:169] op_sel_hi:[1,0]
	v_cvt_pk_bf16_f32 v90, v96, v97
	v_cvt_pk_bf16_f32 v91, v98, v99
	global_store_dwordx4 v[160:161], v[88:91], off
	s_nop 1
	v_pk_mul_f32 v[88:89], v[82:83], v[168:169] op_sel_hi:[1,0]
	v_pk_mul_f32 v[82:83], v[80:81], v[168:169] op_sel_hi:[1,0]
	v_cvt_pk_bf16_f32 v80, v84, v85
	v_fmamk_f32 v84, v231, 0x39800000, v152
	v_rsq_f32_e32 v84, v84
	v_cvt_pk_bf16_f32 v81, v86, v87
	v_cvt_pk_bf16_f32 v82, v82, v83
	v_cvt_pk_bf16_f32 v83, v88, v89
	global_store_dwordx4 v[160:161], v[80:83], off offset:256
	s_nop 1
	v_mul_f32_e32 v80, v174, v84
	v_lshlrev_b64 v[82:83], 13, v[158:159]
	v_lshl_add_u64 v[82:83], v[154:155], 0, v[82:83]
	v_pk_mul_f32 v[78:79], v[78:79], v[80:81] op_sel_hi:[1,0]
	v_pk_mul_f32 v[76:77], v[76:77], v[80:81] op_sel_hi:[1,0]
	v_pk_mul_f32 v[84:85], v[74:75], v[80:81] op_sel_hi:[1,0]
	v_pk_mul_f32 v[74:75], v[72:73], v[80:81] op_sel_hi:[1,0]
	v_cvt_pk_bf16_f32 v72, v76, v77
	v_cvt_pk_bf16_f32 v73, v78, v79
	v_pk_mul_f32 v[68:69], v[68:69], v[80:81] op_sel_hi:[1,0]
	v_cvt_pk_bf16_f32 v74, v74, v75
	v_cvt_pk_bf16_f32 v75, v84, v85
	global_store_dwordx4 v[82:83], v[72:75], off
	v_pk_mul_f32 v[70:71], v[70:71], v[80:81] op_sel_hi:[1,0]
	s_nop 0
	v_pk_mul_f32 v[72:73], v[66:67], v[80:81] op_sel_hi:[1,0]
	v_pk_mul_f32 v[66:67], v[64:65], v[80:81] op_sel_hi:[1,0]
	v_cvt_pk_bf16_f32 v64, v68, v69
	v_fmamk_f32 v68, v232, 0x39800000, v152
	v_rsq_f32_e32 v68, v68
	v_cvt_pk_bf16_f32 v65, v70, v71
	v_cvt_pk_bf16_f32 v66, v66, v67
	v_cvt_pk_bf16_f32 v67, v72, v73
	global_store_dwordx4 v[82:83], v[64:67], off offset:256
	s_nop 1
	v_mul_f32_e32 v64, v174, v68
	v_pk_mul_f32 v[60:61], v[60:61], v[64:65] op_sel_hi:[1,0]
	v_pk_mul_f32 v[68:69], v[58:59], v[64:65] op_sel_hi:[1,0]
	v_pk_mul_f32 v[58:59], v[56:57], v[64:65] op_sel_hi:[1,0]
	v_cvt_pk_bf16_f32 v56, v60, v61
	v_add_co_u32_e32 v60, vcc, s69, v144
	v_pk_mul_f32 v[62:63], v[62:63], v[64:65] op_sel_hi:[1,0]
	s_nop 0
	v_addc_co_u32_e32 v61, vcc, 0, v145, vcc
	v_cvt_pk_bf16_f32 v57, v62, v63
	v_pk_mul_f32 v[52:53], v[52:53], v[64:65] op_sel_hi:[1,0]
	v_cvt_pk_bf16_f32 v58, v58, v59
	v_cvt_pk_bf16_f32 v59, v68, v69
	global_store_dwordx4 v[60:61], v[56:59], off
	v_lshl_add_u64 v[66:67], v[144:145], 0, s[4:5]
	v_pk_mul_f32 v[54:55], v[54:55], v[64:65] op_sel_hi:[1,0]
	v_pk_mul_f32 v[56:57], v[50:51], v[64:65] op_sel_hi:[1,0]
	v_pk_mul_f32 v[50:51], v[48:49], v[64:65] op_sel_hi:[1,0]
	v_cvt_pk_bf16_f32 v48, v52, v53
	v_fmamk_f32 v52, v233, 0x39800000, v152
	v_rsq_f32_e32 v52, v52
	v_cvt_pk_bf16_f32 v49, v54, v55
	v_cvt_pk_bf16_f32 v50, v50, v51
	v_cvt_pk_bf16_f32 v51, v56, v57
	global_store_dwordx4 v[66:67], v[48:51], off offset:256
	s_nop 1
	v_mul_f32_e32 v48, v174, v52
	v_pk_mul_f32 v[44:45], v[44:45], v[48:49] op_sel_hi:[1,0]
	v_pk_mul_f32 v[52:53], v[42:43], v[48:49] op_sel_hi:[1,0]
	v_pk_mul_f32 v[42:43], v[40:41], v[48:49] op_sel_hi:[1,0]
	v_cvt_pk_bf16_f32 v40, v44, v45
	v_add_co_u32_e32 v44, vcc, s70, v144
	v_pk_mul_f32 v[46:47], v[46:47], v[48:49] op_sel_hi:[1,0]
	s_nop 0
	v_addc_co_u32_e32 v45, vcc, 0, v145, vcc
	v_cvt_pk_bf16_f32 v41, v46, v47
	v_pk_mul_f32 v[36:37], v[36:37], v[48:49] op_sel_hi:[1,0]
	v_cvt_pk_bf16_f32 v42, v42, v43
	v_cvt_pk_bf16_f32 v43, v52, v53
	global_store_dwordx4 v[44:45], v[40:43], off
	v_lshl_add_u64 v[50:51], v[144:145], 0, s[14:15]
	v_pk_mul_f32 v[38:39], v[38:39], v[48:49] op_sel_hi:[1,0]
	v_pk_mul_f32 v[40:41], v[34:35], v[48:49] op_sel_hi:[1,0]
	v_pk_mul_f32 v[34:35], v[32:33], v[48:49] op_sel_hi:[1,0]
	v_cvt_pk_bf16_f32 v32, v36, v37
	v_fmamk_f32 v36, v234, 0x39800000, v152
	v_rsq_f32_e32 v36, v36
	v_cvt_pk_bf16_f32 v33, v38, v39
	v_cvt_pk_bf16_f32 v34, v34, v35
	v_cvt_pk_bf16_f32 v35, v40, v41
	global_store_dwordx4 v[50:51], v[32:35], off offset:256
	s_nop 1
	v_mul_f32_e32 v32, v174, v36
	v_pk_mul_f32 v[28:29], v[28:29], v[32:33] op_sel_hi:[1,0]
	v_pk_mul_f32 v[36:37], v[26:27], v[32:33] op_sel_hi:[1,0]
	v_pk_mul_f32 v[26:27], v[24:25], v[32:33] op_sel_hi:[1,0]
	v_cvt_pk_bf16_f32 v24, v28, v29
	v_add_co_u32_e32 v28, vcc, s71, v144
	v_pk_mul_f32 v[30:31], v[30:31], v[32:33] op_sel_hi:[1,0]
	s_nop 0
	v_addc_co_u32_e32 v29, vcc, 0, v145, vcc
	v_cvt_pk_bf16_f32 v25, v30, v31
	v_pk_mul_f32 v[20:21], v[20:21], v[32:33] op_sel_hi:[1,0]
	v_cvt_pk_bf16_f32 v26, v26, v27
	v_cvt_pk_bf16_f32 v27, v36, v37
	global_store_dwordx4 v[28:29], v[24:27], off
	v_lshl_add_u64 v[34:35], v[144:145], 0, s[16:17]
	v_pk_mul_f32 v[22:23], v[22:23], v[32:33] op_sel_hi:[1,0]
	v_pk_mul_f32 v[24:25], v[18:19], v[32:33] op_sel_hi:[1,0]
	v_pk_mul_f32 v[18:19], v[16:17], v[32:33] op_sel_hi:[1,0]
	v_cvt_pk_bf16_f32 v16, v20, v21
	v_fmamk_f32 v20, v235, 0x39800000, v152
	v_rsq_f32_e32 v20, v20
	v_cvt_pk_bf16_f32 v17, v22, v23
	v_cvt_pk_bf16_f32 v18, v18, v19
	v_cvt_pk_bf16_f32 v19, v24, v25
	global_store_dwordx4 v[34:35], v[16:19], off offset:256
	s_nop 1
	v_mul_f32_e32 v16, v174, v20
	v_pk_mul_f32 v[12:13], v[12:13], v[16:17] op_sel_hi:[1,0]
	v_pk_mul_f32 v[20:21], v[10:11], v[16:17] op_sel_hi:[1,0]
	v_pk_mul_f32 v[10:11], v[8:9], v[16:17] op_sel_hi:[1,0]
	v_cvt_pk_bf16_f32 v8, v12, v13
	v_add_co_u32_e32 v12, vcc, s72, v144
	v_pk_mul_f32 v[14:15], v[14:15], v[16:17] op_sel_hi:[1,0]
	s_nop 0
	v_addc_co_u32_e32 v13, vcc, 0, v145, vcc
	v_cvt_pk_bf16_f32 v9, v14, v15
	v_lshl_add_u64 v[18:19], v[144:145], 0, s[18:19]
	v_cvt_pk_bf16_f32 v10, v10, v11
	v_cvt_pk_bf16_f32 v11, v20, v21
	global_store_dwordx4 v[12:13], v[8:11], off
	s_andn2_b64 vcc, exec, s[0:1]
	s_mov_b64 s[0:1], -1
	v_pk_mul_f32 v[8:9], v[2:3], v[16:17] op_sel_hi:[1,0]
	v_pk_mul_f32 v[2:3], v[0:1], v[16:17] op_sel_hi:[1,0]
	v_pk_mul_f32 v[6:7], v[6:7], v[16:17] op_sel_hi:[1,0]
	v_pk_mul_f32 v[4:5], v[4:5], v[16:17] op_sel_hi:[1,0]
	s_nop 0
	v_cvt_pk_bf16_f32 v0, v4, v5
	v_cvt_pk_bf16_f32 v1, v6, v7
	v_cvt_pk_bf16_f32 v2, v2, v3
	v_cvt_pk_bf16_f32 v3, v8, v9
	global_store_dwordx4 v[18:19], v[0:3], off offset:256
	s_cbranch_vccnz .LBB0_180
